# plus near-tile bias lookup chains lose their never-taken far re-tests (s_and/v_mov/s_cbranch per key) and the s_nop pads between dependent v_max3 ops are removed
# speedup vs baseline: 1.0108x; 1.0063x over previous
.LBB0_1145:
	s_waitcnt lgkmcnt(0)
	v_add_f32_e32 v65, v65, v230
	v_cmp_gt_u32_e32 vcc, s46, v187
	v_add_f32_e32 v48, v48, v229
	v_add_f32_e32 v47, v47, v225
	v_cndmask_b32_e32 v187, v137, v65, vcc
	v_cmp_gt_u32_e32 vcc, s46, v228
	v_add_f32_e32 v46, v46, v221
	v_add_f32_e32 v45, v45, v217
	v_cndmask_b32_e32 v228, v137, v48, vcc
	v_add_f32_e32 v48, v64, v227
	v_cmp_gt_u32_e32 vcc, s46, v226
	v_add_f32_e32 v44, v44, v213
	v_add_f32_e32 v43, v43, v209
	v_cndmask_b32_e32 v226, v137, v48, vcc
	v_cmp_gt_u32_e32 vcc, s46, v224
	v_add_f32_e32 v42, v42, v205
	v_add_f32_e32 v41, v41, v201
	v_cndmask_b32_e32 v224, v137, v47, vcc
	v_add_f32_e32 v47, v63, v223
	v_cmp_gt_u32_e32 vcc, s46, v222
	v_add_f32_e32 v40, v40, v197
	v_add_f32_e32 v39, v39, v193
	v_cndmask_b32_e32 v64, v137, v47, vcc
	v_cmp_gt_u32_e32 vcc, s46, v220
	v_add_f32_e32 v38, v38, v189
	v_add_f32_e32 v37, v37, v183
	v_cndmask_b32_e32 v220, v137, v46, vcc
	v_add_f32_e32 v46, v62, v219
	v_cmp_gt_u32_e32 vcc, s46, v218
	v_add_f32_e32 v36, v36, v179
	v_add_f32_e32 v35, v35, v175
	v_cndmask_b32_e32 v62, v137, v46, vcc
	v_cmp_gt_u32_e32 vcc, s46, v216
	v_add_f32_e32 v34, v34, v171
	v_add_f32_e32 v0, v49, v0
	v_cndmask_b32_e32 v48, v137, v45, vcc
	v_add_f32_e32 v45, v61, v215
	v_cmp_gt_u32_e32 vcc, s46, v214
	s_nop 1
	v_cndmask_b32_e32 v214, v137, v45, vcc
	v_cmp_gt_u32_e32 vcc, s46, v212
	s_nop 1
	v_cndmask_b32_e32 v47, v137, v44, vcc
	v_add_f32_e32 v44, v60, v211
	v_cmp_gt_u32_e32 vcc, s46, v210
	s_nop 1
	v_cndmask_b32_e32 v60, v137, v44, vcc
	v_cmp_gt_u32_e32 vcc, s46, v208
	s_nop 1
	v_cndmask_b32_e32 v45, v137, v43, vcc
	v_add_f32_e32 v43, v59, v207
	v_cmp_gt_u32_e32 vcc, s46, v206
	s_nop 1
	v_cndmask_b32_e32 v206, v137, v43, vcc
	v_cmp_gt_u32_e32 vcc, s46, v204
	s_nop 1
	v_cndmask_b32_e32 v43, v137, v42, vcc
	v_add_f32_e32 v42, v58, v203
	v_cmp_gt_u32_e32 vcc, s46, v202
	s_nop 1
	v_cndmask_b32_e32 v58, v137, v42, vcc
	v_cmp_gt_u32_e32 vcc, s46, v200
	s_nop 1
	v_cndmask_b32_e32 v46, v137, v41, vcc
	v_add_f32_e32 v41, v57, v199
	v_cmp_gt_u32_e32 vcc, s46, v198
	s_nop 1
	v_cndmask_b32_e32 v198, v137, v41, vcc
	v_cmp_gt_u32_e32 vcc, s46, v196
	s_nop 1
	v_cndmask_b32_e32 v44, v137, v40, vcc
	v_add_f32_e32 v40, v56, v195
	v_cmp_gt_u32_e32 vcc, s46, v194
	s_nop 1
	v_cndmask_b32_e32 v56, v137, v40, vcc
	v_cmp_gt_u32_e32 vcc, s46, v192
	s_nop 1
	v_cndmask_b32_e32 v42, v137, v39, vcc
	v_add_f32_e32 v39, v55, v191
	v_cmp_gt_u32_e32 vcc, s46, v190
	s_nop 1
	v_cndmask_b32_e32 v55, v137, v39, vcc
	v_cmp_gt_u32_e32 vcc, s46, v188
	s_nop 1
	v_cndmask_b32_e32 v41, v137, v38, vcc
	v_add_f32_e32 v38, v54, v185
	v_cmp_gt_u32_e32 vcc, s46, v184
	s_nop 1
	v_cndmask_b32_e32 v61, v137, v38, vcc
	v_cmp_gt_u32_e32 vcc, s46, v182
	v_add_f32_e32 v38, v53, v181
	s_nop 0
	v_cndmask_b32_e32 v37, v137, v37, vcc
	v_cmp_gt_u32_e32 vcc, s46, v180
	s_nop 1
	v_cndmask_b32_e32 v40, v137, v38, vcc
	v_cmp_gt_u32_e32 vcc, s46, v178
	v_add_f32_e32 v38, v52, v177
	s_nop 0
	v_cndmask_b32_e32 v36, v137, v36, vcc
	v_cmp_gt_u32_e32 vcc, s46, v176
	s_nop 1
	v_cndmask_b32_e32 v39, v137, v38, vcc
	v_cmp_gt_u32_e32 vcc, s46, v174
	s_nop 1
	v_cndmask_b32_e32 v38, v137, v35, vcc
	v_add_f32_e32 v35, v51, v173
	v_cmp_gt_u32_e32 vcc, s46, v172
	s_nop 1
	v_cndmask_b32_e32 v52, v137, v35, vcc
	v_cmp_gt_u32_e32 vcc, s46, v170
	s_nop 1
	v_cndmask_b32_e32 v35, v137, v34, vcc
	v_add_f32_e32 v34, v50, v169
	v_cmp_gt_u32_e32 vcc, s46, v168
	s_nop 1
	v_cndmask_b32_e32 v50, v137, v34, vcc
	v_max3_f32 v34, v137, v50, v35
	v_cmp_gt_u32_e32 vcc, s46, v186
	v_max3_f32 v34, v34, v52, v38
	v_max3_f32 v34, v34, v39, v36
	v_max3_f32 v34, v34, v40, v37
	v_cndmask_b32_e32 v0, v137, v0, vcc
	v_max3_f32 v34, v34, v61, v41
	v_max3_f32 v34, v34, v55, v42
	v_max3_f32 v34, v34, v56, v44
	v_max3_f32 v34, v34, v198, v46
	v_max3_f32 v34, v34, v58, v43
	v_max3_f32 v34, v34, v206, v45
	v_max3_f32 v34, v34, v60, v47
	v_max3_f32 v34, v34, v214, v48
	v_max3_f32 v34, v34, v62, v220
	v_max3_f32 v34, v34, v64, v224
	v_max3_f32 v34, v34, v226, v228
	v_max3_f32 v34, v34, v187, v0
	ds_bpermute_b32 v49, v161, v34
	v_max_f32_e32 v34, v34, v34
	s_waitcnt lgkmcnt(0)
	v_max_f32_e32 v49, v49, v49
	v_max_f32_e32 v171, v34, v49
	v_max_f32_e32 v34, v166, v166
	v_max_f32_e32 v34, v34, v171
	v_sub_f32_e32 v49, v50, v34
	v_sub_f32_e32 v35, v35, v34
	v_exp_f32_e32 v51, v49
	v_exp_f32_e32 v35, v35
	v_sub_f32_e32 v49, v52, v34
	v_sub_f32_e32 v38, v38, v34
	v_exp_f32_e32 v54, v49
	v_exp_f32_e32 v38, v38
	v_sub_f32_e32 v39, v39, v34
	v_sub_f32_e32 v36, v36, v34
	v_add_f32_e32 v49, v51, v35
	v_exp_f32_e32 v57, v39
	v_exp_f32_e32 v39, v36
	v_sub_f32_e32 v36, v40, v34
	v_add_f32_e32 v49, 0, v49
	v_add_f32_e32 v50, v54, v38
	v_exp_f32_e32 v59, v36
	v_sub_f32_e32 v36, v37, v34
	v_exp_f32_e32 v40, v36
	v_add_f32_e32 v36, v50, v49
	v_sub_f32_e32 v49, v61, v34
	v_exp_f32_e32 v61, v49
	v_sub_f32_e32 v41, v41, v34
	v_sub_f32_e32 v49, v55, v34
	v_exp_f32_e32 v41, v41
	v_exp_f32_e32 v63, v49
	v_sub_f32_e32 v42, v42, v34
	v_sub_f32_e32 v49, v56, v34
	v_exp_f32_e32 v42, v42
	v_exp_f32_e32 v65, v49
	v_sub_f32_e32 v44, v44, v34
	v_sub_f32_e32 v49, v198, v34
	v_add_f32_e32 v37, v57, v39
	v_exp_f32_e32 v44, v44
	v_exp_f32_e32 v169, v49
	v_sub_f32_e32 v46, v46, v34
	v_sub_f32_e32 v49, v58, v34
	v_add_f32_e32 v36, v37, v36
	v_add_f32_e32 v37, v59, v40
	v_exp_f32_e32 v46, v46
	v_exp_f32_e32 v52, v49
	v_sub_f32_e32 v43, v43, v34
	v_sub_f32_e32 v49, v206, v34
	v_add_f32_e32 v36, v37, v36
	v_add_f32_e32 v37, v61, v41
	v_exp_f32_e32 v43, v43
	v_exp_f32_e32 v55, v49
	v_sub_f32_e32 v45, v45, v34
	v_sub_f32_e32 v49, v60, v34
	v_add_f32_e32 v36, v37, v36
	v_add_f32_e32 v37, v63, v42
	v_exp_f32_e32 v45, v45
	v_exp_f32_e32 v58, v49
	v_sub_f32_e32 v47, v47, v34
	v_sub_f32_e32 v49, v214, v34
	v_add_f32_e32 v36, v37, v36
	v_add_f32_e32 v37, v65, v44
	v_exp_f32_e32 v47, v47
	v_exp_f32_e32 v60, v49
	v_sub_f32_e32 v48, v48, v34
	v_sub_f32_e32 v49, v62, v34
	v_add_f32_e32 v36, v37, v36
	v_add_f32_e32 v37, v169, v46
	v_exp_f32_e32 v48, v48
	v_exp_f32_e32 v62, v49
	v_sub_f32_e32 v49, v220, v34
	v_sub_f32_e32 v50, v64, v34
	v_add_f32_e32 v36, v37, v36
	v_add_f32_e32 v37, v52, v43
	v_exp_f32_e32 v49, v49
	v_exp_f32_e32 v64, v50
	v_sub_f32_e32 v50, v224, v34
	v_sub_f32_e32 v53, v226, v34
	v_add_f32_e32 v36, v37, v36
	v_add_f32_e32 v37, v55, v45
	v_exp_f32_e32 v50, v50
	v_exp_f32_e32 v168, v53
	v_sub_f32_e32 v53, v228, v34
	v_add_f32_e32 v36, v37, v36
	v_add_f32_e32 v37, v58, v47
	v_exp_f32_e32 v53, v53
	v_sub_f32_e32 v56, v187, v34
	v_sub_f32_e32 v0, v0, v34
	v_add_f32_e32 v36, v37, v36
	v_add_f32_e32 v37, v60, v48
	v_exp_f32_e32 v170, v56
	v_exp_f32_e32 v56, v0
	v_add_f32_e32 v36, v37, v36
	v_add_f32_e32 v37, v62, v49
	v_add_f32_e32 v36, v37, v36
	v_add_f32_e32 v37, v64, v50
	v_add_f32_e32 v0, v37, v36
	v_add_f32_e32 v36, v168, v53
	v_add_f32_e32 v0, v36, v0
	v_add_f32_e32 v36, v170, v56
	v_add_f32_e32 v36, v36, v0
	v_sub_f32_e32 v172, v166, v34
	ds_bpermute_b32 v37, v161, v36
	v_exp_f32_e32 v0, v172
	v_cmp_gt_f32_e32 vcc, v171, v166
	s_cbranch_vccz .LBB0_1147
	v_pk_mul_f32 v[32:33], v[134:135], v[0:1] op_sel_hi:[1,0]
	v_pk_mul_f32 v[30:31], v[132:133], v[0:1] op_sel_hi:[1,0]
	v_pk_mul_f32 v[28:29], v[130:131], v[0:1] op_sel_hi:[1,0]
	v_pk_mul_f32 v[26:27], v[128:129], v[0:1] op_sel_hi:[1,0]
	v_pk_mul_f32 v[24:25], v[126:127], v[0:1] op_sel_hi:[1,0]
	v_pk_mul_f32 v[22:23], v[124:125], v[0:1] op_sel_hi:[1,0]
	v_pk_mul_f32 v[20:21], v[122:123], v[0:1] op_sel_hi:[1,0]
	v_pk_mul_f32 v[18:19], v[120:121], v[0:1] op_sel_hi:[1,0]
	v_pk_mul_f32 v[16:17], v[118:119], v[0:1] op_sel_hi:[1,0]
	v_pk_mul_f32 v[14:15], v[116:117], v[0:1] op_sel_hi:[1,0]
	v_pk_mul_f32 v[12:13], v[114:115], v[0:1] op_sel_hi:[1,0]
	v_pk_mul_f32 v[10:11], v[112:113], v[0:1] op_sel_hi:[1,0]
	v_pk_mul_f32 v[8:9], v[110:111], v[0:1] op_sel_hi:[1,0]
	v_pk_mul_f32 v[6:7], v[108:109], v[0:1] op_sel_hi:[1,0]
	v_pk_mul_f32 v[4:5], v[106:107], v[0:1] op_sel_hi:[1,0]
	v_pk_mul_f32 v[2:3], v[104:105], v[0:1] op_sel_hi:[1,0]

.LBB0_1151:
	v_med3_i32 v171, v170, 0, v138
	v_lshl_add_u32 v171, v171, 2, s3
	ds_read_b32 v171, v171
	v_add_u32_e32 v172, v187, v144
.LBB0_1152:
	v_med3_i32 v173, v172, 0, v138
	v_lshl_add_u32 v173, v173, 2, s3
	ds_read_b32 v173, v173
	v_add_u32_e32 v174, v186, v144
.LBB0_1153:
	v_med3_i32 v175, v174, 0, v138
	v_lshl_add_u32 v175, v175, 2, s3
	ds_read_b32 v175, v175
	v_add_u32_e32 v176, v187, v145
.LBB0_1154:
	v_med3_i32 v177, v176, 0, v138
	v_lshl_add_u32 v177, v177, 2, s3
	ds_read_b32 v177, v177
	v_add_u32_e32 v178, v186, v145
.LBB0_1155:
	v_med3_i32 v179, v178, 0, v138
	v_lshl_add_u32 v179, v179, 2, s3
	ds_read_b32 v179, v179
	v_add_u32_e32 v180, v187, v146
.LBB0_1156:
	v_med3_i32 v181, v180, 0, v138
	v_lshl_add_u32 v181, v181, 2, s3
	ds_read_b32 v181, v181
	v_add_u32_e32 v182, v186, v146
.LBB0_1157:
	v_med3_i32 v183, v182, 0, v138
	v_lshl_add_u32 v183, v183, 2, s3
	ds_read_b32 v183, v183
	v_add_u32_e32 v184, v187, v147
.LBB0_1158:
	v_med3_i32 v185, v184, 0, v138
	v_lshl_add_u32 v185, v185, 2, s3
	ds_read_b32 v185, v185
	v_add_u32_e32 v188, v186, v147
.LBB0_1159:
	v_med3_i32 v189, v188, 0, v138
	v_lshl_add_u32 v189, v189, 2, s3
	ds_read_b32 v189, v189
	v_add_u32_e32 v190, v187, v148
.LBB0_1160:
	v_med3_i32 v191, v190, 0, v138
	v_lshl_add_u32 v191, v191, 2, s3
	ds_read_b32 v191, v191
	v_add_u32_e32 v192, v186, v148
.LBB0_1161:
	v_med3_i32 v193, v192, 0, v138
	v_lshl_add_u32 v193, v193, 2, s3
	ds_read_b32 v193, v193
	v_add_u32_e32 v194, v187, v149
.LBB0_1162:
	v_med3_i32 v195, v194, 0, v138
	v_lshl_add_u32 v195, v195, 2, s3
	ds_read_b32 v195, v195
	v_add_u32_e32 v196, v186, v149
.LBB0_1163:
	v_med3_i32 v197, v196, 0, v138
	v_lshl_add_u32 v197, v197, 2, s3
	ds_read_b32 v197, v197
	v_add_u32_e32 v198, v187, v150
.LBB0_1164:
	v_med3_i32 v199, v198, 0, v138
	v_lshl_add_u32 v199, v199, 2, s3
	ds_read_b32 v199, v199
	v_add_u32_e32 v200, v186, v150
.LBB0_1165:
	v_med3_i32 v201, v200, 0, v138
	v_lshl_add_u32 v201, v201, 2, s3
	ds_read_b32 v201, v201
	v_add_u32_e32 v202, v187, v151
.LBB0_1166:
	v_med3_i32 v203, v202, 0, v138
	v_lshl_add_u32 v203, v203, 2, s3
	ds_read_b32 v203, v203
	v_add_u32_e32 v204, v186, v151
.LBB0_1167:
	v_med3_i32 v205, v204, 0, v138
	v_lshl_add_u32 v205, v205, 2, s3
	ds_read_b32 v205, v205
	v_add_u32_e32 v206, v187, v152
.LBB0_1168:
	v_med3_i32 v207, v206, 0, v138
	v_lshl_add_u32 v207, v207, 2, s3
	ds_read_b32 v207, v207
	v_add_u32_e32 v208, v186, v152
.LBB0_1169:
	v_med3_i32 v209, v208, 0, v138
	v_lshl_add_u32 v209, v209, 2, s3
	ds_read_b32 v209, v209
	v_add_u32_e32 v210, v187, v153
.LBB0_1170:
	v_med3_i32 v211, v210, 0, v138
	v_lshl_add_u32 v211, v211, 2, s3
	ds_read_b32 v211, v211
	v_add_u32_e32 v212, v186, v153
.LBB0_1171:
	v_med3_i32 v213, v212, 0, v138
	v_lshl_add_u32 v213, v213, 2, s3
	ds_read_b32 v213, v213
	v_add_u32_e32 v214, v187, v154
.LBB0_1172:
	v_med3_i32 v215, v214, 0, v138
	v_lshl_add_u32 v215, v215, 2, s3
	ds_read_b32 v215, v215
	v_add_u32_e32 v216, v186, v154
.LBB0_1173:
	v_med3_i32 v217, v216, 0, v138
	v_lshl_add_u32 v217, v217, 2, s3
	ds_read_b32 v217, v217
	v_add_u32_e32 v218, v187, v155
.LBB0_1174:
	v_med3_i32 v219, v218, 0, v138
	v_lshl_add_u32 v219, v219, 2, s3
	ds_read_b32 v219, v219
	v_add_u32_e32 v220, v186, v155
.LBB0_1175:
	v_med3_i32 v221, v220, 0, v138
	v_lshl_add_u32 v221, v221, 2, s3
	ds_read_b32 v221, v221
	v_add_u32_e32 v222, v187, v156
.LBB0_1176:
	v_med3_i32 v223, v222, 0, v138
	v_lshl_add_u32 v223, v223, 2, s3
	ds_read_b32 v223, v223
	v_add_u32_e32 v224, v186, v156
.LBB0_1177:
	v_med3_i32 v225, v224, 0, v138
	v_lshl_add_u32 v225, v225, 2, s3
	ds_read_b32 v225, v225
	v_add_u32_e32 v226, v187, v157
.LBB0_1178:
	v_med3_i32 v227, v226, 0, v138
	v_lshl_add_u32 v227, v227, 2, s3
	ds_read_b32 v227, v227
	v_add_u32_e32 v228, v186, v157
.LBB0_1179:
	v_med3_i32 v229, v228, 0, v138
	v_lshl_add_u32 v229, v229, 2, s3
	ds_read_b32 v229, v229
	v_add_u32_e32 v187, v187, v158
.LBB0_1180:
	v_med3_i32 v230, v187, 0, v138
	v_lshl_add_u32 v230, v230, 2, s3
	ds_read_b32 v230, v230
	s_and_b64 vcc, exec, s[8:9]
	v_add_u32_e32 v186, v186, v158
	s_cbranch_vccz .LBB0_1144
	s_branch .LBB0_1145

.LBB0_1316:
	s_or_b64 exec, exec, s[8:9]
	v_max3_f32 v17, v191, v44, v43
	v_lshlrev_b32_e32 v33, 7, v0
	v_max3_f32 v17, v17, v18, v2
	v_lshlrev_b32_e32 v45, 2, v85
	v_max3_f32 v17, v17, v19, v3
	s_movk_i32 s8, 0x80
	v_max3_f32 v17, v17, v20, v4
	v_bitop3_b32 v197, v33, s8, v45 bitop3:0x36
	v_max3_f32 v17, v17, v21, v5
	v_mov_b32_e32 v79, 0xf149f2ca
	v_max3_f32 v17, v17, v22, v6
	v_max3_f32 v17, v17, v23, v7
	v_max3_f32 v17, v17, v24, v8
	v_max3_f32 v17, v17, v25, v9
	v_max3_f32 v17, v17, v26, v10
	v_max3_f32 v17, v17, v27, v11
	v_max3_f32 v17, v17, v28, v12
	v_max3_f32 v17, v17, v29, v13
	v_max3_f32 v17, v17, v30, v14
	v_max3_f32 v17, v17, v31, v15
	v_max3_f32 v17, v17, v32, v16
	ds_bpermute_b32 v33, v197, v17
	v_max_f32_e32 v17, v17, v17
	s_waitcnt lgkmcnt(0)
	v_max_f32_e32 v33, v33, v33
	v_max_f32_e32 v17, v17, v33
	v_max_f32_e32 v75, 0xf149f2ca, v17
	v_sub_f32_e32 v5, v5, v75
	v_exp_f32_e32 v59, v5
	v_sub_f32_e32 v5, v22, v75
	v_exp_f32_e32 v22, v5
	v_sub_f32_e32 v5, v6, v75
	v_exp_f32_e32 v60, v5
	v_sub_f32_e32 v5, v23, v75
	v_exp_f32_e32 v23, v5
	v_sub_f32_e32 v5, v7, v75
	v_sub_f32_e32 v33, v44, v75
	v_sub_f32_e32 v43, v43, v75
	v_exp_f32_e32 v61, v5
	v_sub_f32_e32 v5, v24, v75
	v_exp_f32_e32 v33, v33
	v_exp_f32_e32 v43, v43
	v_sub_f32_e32 v18, v18, v75
	v_sub_f32_e32 v2, v2, v75
	v_sub_f32_e32 v3, v3, v75
	v_exp_f32_e32 v24, v5
	v_sub_f32_e32 v5, v8, v75
	v_exp_f32_e32 v18, v18
	v_exp_f32_e32 v56, v2
	v_sub_f32_e32 v19, v19, v75
	v_exp_f32_e32 v57, v3
	v_sub_f32_e32 v3, v20, v75
	v_exp_f32_e32 v62, v5
	v_sub_f32_e32 v5, v25, v75
	v_exp_f32_e32 v19, v19
	v_exp_f32_e32 v20, v3
	v_sub_f32_e32 v3, v4, v75
	v_exp_f32_e32 v63, v5
	v_sub_f32_e32 v5, v9, v75
	v_exp_f32_e32 v58, v3
	v_sub_f32_e32 v21, v21, v75
	v_exp_f32_e32 v64, v5
	v_sub_f32_e32 v5, v26, v75
	v_add_f32_e32 v44, v33, v43
	v_exp_f32_e32 v21, v21
	v_exp_f32_e32 v65, v5
	v_sub_f32_e32 v5, v10, v75
	v_add_f32_e32 v44, 0, v44
	v_add_f32_e32 v45, v18, v56
	v_exp_f32_e32 v66, v5
	v_sub_f32_e32 v5, v27, v75
	v_add_f32_e32 v3, v45, v44
	v_add_f32_e32 v4, v19, v57
	v_exp_f32_e32 v67, v5
	v_sub_f32_e32 v5, v11, v75
	v_add_f32_e32 v3, v4, v3
	v_add_f32_e32 v4, v20, v58
	v_exp_f32_e32 v68, v5
	v_sub_f32_e32 v5, v28, v75
	v_add_f32_e32 v3, v4, v3
	v_add_f32_e32 v4, v21, v59
	v_exp_f32_e32 v69, v5
	v_sub_f32_e32 v5, v12, v75
	v_add_f32_e32 v3, v4, v3
	v_add_f32_e32 v4, v22, v60
	v_exp_f32_e32 v70, v5
	v_sub_f32_e32 v5, v29, v75
	v_add_f32_e32 v3, v4, v3
	v_add_f32_e32 v4, v23, v61
	v_exp_f32_e32 v71, v5
	v_sub_f32_e32 v5, v13, v75
	v_add_f32_e32 v3, v4, v3
	v_add_f32_e32 v4, v24, v62
	v_exp_f32_e32 v72, v5
	v_sub_f32_e32 v5, v30, v75
	v_add_f32_e32 v3, v4, v3
	v_add_f32_e32 v4, v63, v64
	v_exp_f32_e32 v73, v5
	v_sub_f32_e32 v5, v14, v75
	v_add_f32_e32 v3, v4, v3
	v_add_f32_e32 v4, v65, v66
	v_exp_f32_e32 v80, v5
	v_add_f32_e32 v3, v4, v3
	v_add_f32_e32 v4, v67, v68
	v_add_f32_e32 v3, v4, v3
	v_add_f32_e32 v4, v69, v70
	v_add_f32_e32 v3, v4, v3
	v_add_f32_e32 v4, v71, v72
	v_add_f32_e32 v3, v4, v3
	v_add_f32_e32 v4, v73, v80
	v_add_f32_e32 v3, v4, v3
	v_sub_f32_e32 v4, v31, v75
	v_exp_f32_e32 v81, v4
	v_sub_f32_e32 v4, v15, v75
	v_exp_f32_e32 v90, v4
	v_sub_f32_e32 v4, v32, v75
	v_exp_f32_e32 v91, v4
	v_sub_f32_e32 v4, v16, v75
	v_exp_f32_e32 v92, v4
	v_sub_f32_e32 v2, 0xf149f2ca, v75
	v_add_f32_e32 v4, v81, v90
	v_add_f32_e32 v3, v4, v3
	v_exp_f32_e32 v2, v2
	v_add_f32_e32 v4, v91, v92
	v_add_f32_e32 v76, v4, v3
	ds_bpermute_b32 v77, v197, v76
	v_cmp_gt_f32_e32 vcc, v17, v79
	s_cmp_lg_u64 vcc, 0
	v_mul_f32_e32 v78, 0, v2
	s_cselect_b64 vcc, -1, 0
	v_cndmask_b32_e32 v2, 0, v78, vcc
	v_mov_b32_e32 v3, v2
	v_mov_b32_e32 v4, v2
	v_mov_b32_e32 v5, v2
	v_mov_b32_e32 v6, v2
	v_mov_b32_e32 v7, v2
	v_mov_b32_e32 v8, v2
	v_mov_b32_e32 v9, v2
	v_mov_b32_e32 v10, v2
	v_mov_b32_e32 v11, v2
	v_mov_b32_e32 v12, v2
	v_mov_b32_e32 v13, v2
	v_mov_b32_e32 v14, v2
	v_mov_b32_e32 v15, v2
	v_mov_b32_e32 v16, v2
	v_mov_b32_e32 v17, v2
	ds_read_b64_tr_b16 v[44:45], v89 offset:12288
	ds_read_b64_tr_b16 v[46:47], v89 offset:13824
	ds_read_b64_tr_b16 v[50:51], v89 offset:13888
	ds_read_b64_tr_b16 v[48:49], v89 offset:12352
	v_cvt_pk_bf16_f32 v52, v33, v18
	v_cvt_pk_bf16_f32 v53, v19, v20
	v_cvt_pk_bf16_f32 v54, v21, v22
	v_cvt_pk_bf16_f32 v55, v23, v24
	s_nop 1
	v_mfma_f32_32x32x16_bf16 v[18:33], v[34:37], v[52:55], v[2:17]
	v_mfma_f32_32x32x16_bf16 v[2:17], v[38:41], v[52:55], v[2:17]
	ds_read_b64_tr_b16 v[34:35], v89 offset:15360
	ds_read_b64_tr_b16 v[36:37], v89 offset:16896
	ds_read_b64_tr_b16 v[40:41], v89 offset:16960
	ds_read_b64_tr_b16 v[38:39], v89 offset:15424
	v_cvt_pk_bf16_f32 v52, v63, v65
	v_cvt_pk_bf16_f32 v53, v67, v69
	v_cvt_pk_bf16_f32 v54, v71, v73
	v_cvt_pk_bf16_f32 v55, v81, v91
	s_waitcnt lgkmcnt(6)
	s_nop 0
	v_mfma_f32_32x32x16_bf16 v[18:33], v[44:47], v[52:55], v[18:33]
	s_waitcnt lgkmcnt(4)
	v_mfma_f32_32x32x16_bf16 v[2:17], v[48:51], v[52:55], v[2:17]
	ds_read_b64_tr_b16 v[44:45], v89 offset:18432
	ds_read_b64_tr_b16 v[46:47], v89 offset:19968
	ds_read_b64_tr_b16 v[50:51], v89 offset:20032
	ds_read_b64_tr_b16 v[48:49], v89 offset:18496
	v_cvt_pk_bf16_f32 v52, v43, v56
	v_cvt_pk_bf16_f32 v53, v57, v58
	v_cvt_pk_bf16_f32 v54, v59, v60
	v_cvt_pk_bf16_f32 v55, v61, v62
	s_waitcnt lgkmcnt(6)
	s_nop 0
	v_mfma_f32_32x32x16_bf16 v[18:33], v[34:37], v[52:55], v[18:33]
	s_waitcnt lgkmcnt(4)
	v_mfma_f32_32x32x16_bf16 v[2:17], v[38:41], v[52:55], v[2:17]
	v_cvt_pk_bf16_f32 v34, v64, v66
	v_cvt_pk_bf16_f32 v35, v68, v70
	v_cvt_pk_bf16_f32 v36, v72, v80
	v_cvt_pk_bf16_f32 v37, v90, v92
	s_waitcnt lgkmcnt(2)
	s_nop 0
	v_mfma_f32_32x32x16_bf16 v[18:33], v[44:47], v[34:37], v[18:33]
	s_waitcnt lgkmcnt(0)
	v_mfma_f32_32x32x16_bf16 v[2:17], v[48:51], v[34:37], v[2:17]
	ds_read_b128 v[34:37], v42 offset:21504
	ds_read_b128 v[66:69], v42 offset:21536
	ds_read_b128 v[38:41], v42 offset:26112
	ds_read_b128 v[70:73], v42 offset:26144
	ds_read_b128 v[90:93], v42 offset:21568
	ds_read_b128 v[94:97], v42 offset:21600
	ds_read_b128 v[114:117], v42 offset:26176
	ds_read_b128 v[118:121], v42 offset:26208
	s_waitcnt lgkmcnt(7)
	v_mfma_f32_32x32x16_bf16 v[50:65], v[34:37], v[98:101], 0
	s_waitcnt lgkmcnt(5)
	v_mfma_f32_32x32x16_bf16 v[34:49], v[38:41], v[98:101], 0
	v_mfma_f32_32x32x16_bf16 v[50:65], v[66:69], v[102:105], v[50:65]
	s_waitcnt lgkmcnt(4)
	v_mfma_f32_32x32x16_bf16 v[34:49], v[70:73], v[102:105], v[34:49]
	s_waitcnt lgkmcnt(3)
	v_mfma_f32_32x32x16_bf16 v[50:65], v[90:93], v[106:109], v[50:65]
	ds_read_b64_tr_b16 v[66:67], v89 offset:30720
	ds_read_b64_tr_b16 v[68:69], v89 offset:32256
	ds_read_b64_tr_b16 v[72:73], v89 offset:32320
	ds_read_b64_tr_b16 v[70:71], v89 offset:30784
	v_add_u32_e32 v81, 0xfffffbe1, v74
	v_cmp_lt_i32_e64 s[8:9], -1, v81
	v_cmp_gt_i32_e32 vcc, 16, v0
	s_and_b64 s[10:11], vcc, s[8:9]
	v_mov_b32_e32 v80, 0xf149f2ca
	s_waitcnt lgkmcnt(5)
	v_mfma_f32_32x32x16_bf16 v[34:49], v[114:117], v[106:109], v[34:49]
	v_mfma_f32_32x32x16_bf16 v[50:65], v[94:97], v[110:113], v[50:65]
	s_waitcnt lgkmcnt(4)
	v_mfma_f32_32x32x16_bf16 v[34:49], v[118:121], v[110:113], v[34:49]
	s_and_saveexec_b64 s[8:9], s[10:11]
	s_cbranch_execz .LBB0_1318
	v_min_u32_e32 v80, 0x7f, v81
	v_lshl_add_u32 v80, v80, 2, s3
	ds_read_b32 v80, v80
	s_waitcnt lgkmcnt(0)
	s_nop 3
	v_add_f32_e32 v80, v50, v80

.LBB0_1380:
	s_or_b64 exec, exec, s[8:9]
	v_max3_f32 v0, v191, v80, v79
	v_max_f32_e32 v65, v75, v75
	v_max3_f32 v0, v0, v50, v34
	v_max3_f32 v0, v0, v51, v35
	v_max3_f32 v0, v0, v52, v36
	v_max3_f32 v0, v0, v53, v37
	v_max3_f32 v0, v0, v54, v38
	v_max3_f32 v0, v0, v55, v39
	v_max3_f32 v0, v0, v56, v40
	v_max3_f32 v0, v0, v57, v41
	v_max3_f32 v0, v0, v58, v42
	v_max3_f32 v0, v0, v59, v43
	v_max3_f32 v0, v0, v60, v44
	v_max3_f32 v0, v0, v61, v45
	v_max3_f32 v0, v0, v62, v46
	v_max3_f32 v0, v0, v63, v47
	v_max3_f32 v0, v0, v64, v48
	ds_bpermute_b32 v49, v197, v0
	v_max_f32_e32 v0, v0, v0
	s_waitcnt lgkmcnt(0)
	v_max_f32_e32 v49, v49, v49
	v_max_f32_e32 v49, v0, v49
	v_max_f32_e32 v118, v65, v49
	v_sub_f32_e32 v35, v35, v118
	v_exp_f32_e32 v92, v35
	v_sub_f32_e32 v35, v52, v118
	v_exp_f32_e32 v125, v35
	v_sub_f32_e32 v35, v36, v118
	v_sub_f32_e32 v36, v53, v118
	v_exp_f32_e32 v136, v36
	v_sub_f32_e32 v36, v37, v118
	v_exp_f32_e32 v94, v36
	v_sub_f32_e32 v36, v54, v118
	v_exp_f32_e32 v138, v36
	v_sub_f32_e32 v36, v38, v118
	v_exp_f32_e32 v95, v36
	v_sub_f32_e32 v36, v55, v118
	v_exp_f32_e32 v141, v36
	v_sub_f32_e32 v36, v39, v118
	v_exp_f32_e32 v96, v36
	v_sub_f32_e32 v36, v56, v118
	v_sub_f32_e32 v0, v80, v118
	v_exp_f32_e32 v142, v36
	v_sub_f32_e32 v36, v40, v118
	v_sub_f32_e32 v65, v79, v118
	v_exp_f32_e32 v116, v0
	v_sub_f32_e32 v0, v50, v118
	v_exp_f32_e32 v97, v36
	v_sub_f32_e32 v36, v57, v118
	v_exp_f32_e32 v90, v65
	v_exp_f32_e32 v119, v0
	v_sub_f32_e32 v0, v34, v118
	v_exp_f32_e32 v120, v36
	v_sub_f32_e32 v36, v41, v118
	v_exp_f32_e32 v91, v0
	v_sub_f32_e32 v51, v51, v118
	v_exp_f32_e32 v114, v36
	v_sub_f32_e32 v36, v58, v118
	v_exp_f32_e32 v123, v51
	v_exp_f32_e32 v122, v36
	v_sub_f32_e32 v36, v42, v118
	v_exp_f32_e32 v93, v35
	v_exp_f32_e32 v115, v36
	v_sub_f32_e32 v36, v59, v118
	v_add_f32_e32 v34, v116, v90
	v_exp_f32_e32 v126, v36
	v_sub_f32_e32 v36, v43, v118
	v_add_f32_e32 v34, 0, v34
	v_add_f32_e32 v50, v119, v91
	v_exp_f32_e32 v117, v36
	v_sub_f32_e32 v36, v60, v118
	v_add_f32_e32 v34, v50, v34
	v_add_f32_e32 v35, v123, v92
	v_exp_f32_e32 v128, v36
	v_sub_f32_e32 v36, v44, v118
	v_add_f32_e32 v34, v35, v34
	v_add_f32_e32 v35, v125, v93
	v_exp_f32_e32 v121, v36
	v_sub_f32_e32 v36, v61, v118
	v_add_f32_e32 v34, v35, v34
	v_add_f32_e32 v35, v136, v94
	v_exp_f32_e32 v139, v36
	v_sub_f32_e32 v36, v45, v118
	v_add_f32_e32 v34, v35, v34
	v_add_f32_e32 v35, v138, v95
	v_exp_f32_e32 v124, v36
	v_sub_f32_e32 v36, v62, v118
	v_add_f32_e32 v34, v35, v34
	v_add_f32_e32 v35, v141, v96
	v_exp_f32_e32 v140, v36
	v_sub_f32_e32 v36, v46, v118
	v_add_f32_e32 v34, v35, v34
	v_add_f32_e32 v35, v142, v97
	v_exp_f32_e32 v127, v36
	v_sub_f32_e32 v36, v63, v118
	v_add_f32_e32 v34, v35, v34
	v_add_f32_e32 v35, v120, v114
	v_exp_f32_e32 v143, v36
	v_sub_f32_e32 v36, v47, v118
	v_add_f32_e32 v34, v35, v34
	v_add_f32_e32 v35, v122, v115
	v_exp_f32_e32 v129, v36
	v_sub_f32_e32 v36, v64, v118
	v_add_f32_e32 v34, v35, v34
	v_add_f32_e32 v35, v126, v117
	v_exp_f32_e32 v144, v36
	v_sub_f32_e32 v36, v48, v118
	v_add_f32_e32 v34, v35, v34
	v_add_f32_e32 v35, v128, v121
	v_exp_f32_e32 v137, v36
	v_add_f32_e32 v34, v35, v34
	v_add_f32_e32 v35, v139, v124
	v_add_f32_e32 v34, v35, v34
	v_add_f32_e32 v35, v140, v127
	v_add_f32_e32 v34, v35, v34
	v_add_f32_e32 v35, v143, v129
	v_add_f32_e32 v34, v35, v34
	v_add_f32_e32 v35, v144, v137
	v_add_f32_e32 v34, v35, v34
	v_sub_f32_e32 v0, v75, v118
	ds_bpermute_b32 v35, v197, v34
	v_exp_f32_e32 v0, v0
	v_cmp_gt_f32_e32 vcc, v49, v75
	s_cbranch_vccz .LBB0_1382
	v_pk_mul_f32 v[32:33], v[32:33], v[0:1] op_sel_hi:[1,0]
	v_pk_mul_f32 v[30:31], v[30:31], v[0:1] op_sel_hi:[1,0]
	v_pk_mul_f32 v[28:29], v[28:29], v[0:1] op_sel_hi:[1,0]
	v_pk_mul_f32 v[26:27], v[26:27], v[0:1] op_sel_hi:[1,0]
	v_pk_mul_f32 v[24:25], v[24:25], v[0:1] op_sel_hi:[1,0]
	v_pk_mul_f32 v[22:23], v[22:23], v[0:1] op_sel_hi:[1,0]
	v_pk_mul_f32 v[20:21], v[20:21], v[0:1] op_sel_hi:[1,0]
	v_pk_mul_f32 v[18:19], v[18:19], v[0:1] op_sel_hi:[1,0]
	v_pk_mul_f32 v[16:17], v[16:17], v[0:1] op_sel_hi:[1,0]
	v_pk_mul_f32 v[14:15], v[14:15], v[0:1] op_sel_hi:[1,0]
	v_pk_mul_f32 v[12:13], v[12:13], v[0:1] op_sel_hi:[1,0]
	v_pk_mul_f32 v[10:11], v[10:11], v[0:1] op_sel_hi:[1,0]
	v_pk_mul_f32 v[8:9], v[8:9], v[0:1] op_sel_hi:[1,0]
	v_pk_mul_f32 v[6:7], v[6:7], v[0:1] op_sel_hi:[1,0]
	v_pk_mul_f32 v[4:5], v[4:5], v[0:1] op_sel_hi:[1,0]
	v_pk_mul_f32 v[2:3], v[2:3], v[0:1] op_sel_hi:[1,0]

.LBB0_1502:
	v_max3_f32 v34, v191, v66, v82
	s_nop 8
	v_max_f32_e32 v36, v177, v177
	v_max3_f32 v34, v34, v67, v83
	v_max3_f32 v34, v34, v68, v84
	v_max3_f32 v34, v34, v69, v85
	v_max3_f32 v34, v34, v70, v86
	v_max3_f32 v34, v34, v71, v87
	v_max3_f32 v34, v34, v72, v88
	v_max3_f32 v34, v34, v73, v89
	v_max3_f32 v34, v34, v74, v90
	v_max3_f32 v34, v34, v75, v91
	v_max3_f32 v34, v34, v76, v92
	v_max3_f32 v34, v34, v77, v93
	v_max3_f32 v34, v34, v78, v94
	v_max3_f32 v34, v34, v79, v95
	v_max3_f32 v34, v34, v80, v96
	v_max3_f32 v34, v34, v81, v97
	ds_bpermute_b32 v35, v197, v34
	v_max_f32_e32 v34, v34, v34
	s_waitcnt lgkmcnt(0)
	v_max_f32_e32 v35, v35, v35
	v_max_f32_e32 v174, v34, v35
	v_max_f32_e32 v35, v36, v174
	v_sub_f32_e32 v34, v66, v35
	v_sub_f32_e32 v36, v82, v35
	v_exp_f32_e32 v53, v34
	v_sub_f32_e32 v34, v67, v35
	v_exp_f32_e32 v36, v36
	v_exp_f32_e32 v55, v34
	v_sub_f32_e32 v34, v83, v35
	v_sub_f32_e32 v40, v68, v35
	v_exp_f32_e32 v39, v34
	v_exp_f32_e32 v58, v40
	v_sub_f32_e32 v40, v84, v35
	v_sub_f32_e32 v41, v69, v35
	v_exp_f32_e32 v40, v40
	v_exp_f32_e32 v60, v41
	v_sub_f32_e32 v41, v85, v35
	v_sub_f32_e32 v42, v70, v35
	v_sub_f32_e32 v44, v72, v35
	v_exp_f32_e32 v41, v41
	v_exp_f32_e32 v62, v42
	v_sub_f32_e32 v42, v86, v35
	v_sub_f32_e32 v43, v71, v35
	v_exp_f32_e32 v66, v44
	v_sub_f32_e32 v44, v88, v35
	v_add_f32_e32 v37, v53, v36
	v_exp_f32_e32 v42, v42
	v_exp_f32_e32 v64, v43
	v_sub_f32_e32 v43, v87, v35
	v_exp_f32_e32 v45, v44
	v_sub_f32_e32 v44, v73, v35
	v_add_f32_e32 v37, 0, v37
	v_add_f32_e32 v38, v55, v39
	v_exp_f32_e32 v43, v43
	v_exp_f32_e32 v68, v44
	v_sub_f32_e32 v44, v89, v35
	v_add_f32_e32 v37, v38, v37
	v_add_f32_e32 v38, v58, v40
	v_exp_f32_e32 v47, v44
	v_sub_f32_e32 v44, v74, v35
	v_add_f32_e32 v37, v38, v37
	v_add_f32_e32 v38, v60, v41
	v_exp_f32_e32 v52, v44
	v_sub_f32_e32 v44, v90, v35
	v_sub_f32_e32 v46, v75, v35
	v_add_f32_e32 v37, v38, v37
	v_add_f32_e32 v38, v62, v42
	v_exp_f32_e32 v44, v44
	v_exp_f32_e32 v56, v46
	v_sub_f32_e32 v46, v91, v35
	v_sub_f32_e32 v48, v76, v35
	v_add_f32_e32 v37, v38, v37
	v_add_f32_e32 v38, v64, v43
	v_exp_f32_e32 v46, v46
	v_exp_f32_e32 v59, v48
	v_sub_f32_e32 v48, v92, v35
	v_sub_f32_e32 v49, v77, v35
	v_add_f32_e32 v37, v38, v37
	v_add_f32_e32 v38, v66, v45
	v_exp_f32_e32 v48, v48
	v_exp_f32_e32 v61, v49
	v_sub_f32_e32 v49, v93, v35
	v_sub_f32_e32 v50, v78, v35
	v_add_f32_e32 v37, v38, v37
	v_add_f32_e32 v38, v68, v47
	v_exp_f32_e32 v49, v49
	v_exp_f32_e32 v63, v50
	v_sub_f32_e32 v50, v94, v35
	v_sub_f32_e32 v51, v79, v35
	v_add_f32_e32 v37, v38, v37
	v_add_f32_e32 v38, v52, v44
	v_exp_f32_e32 v50, v50
	v_exp_f32_e32 v65, v51
	v_sub_f32_e32 v51, v95, v35
	v_sub_f32_e32 v54, v80, v35
	v_add_f32_e32 v37, v38, v37
	v_add_f32_e32 v38, v56, v46
	v_exp_f32_e32 v51, v51
	v_exp_f32_e32 v67, v54
	v_sub_f32_e32 v54, v96, v35
	v_sub_f32_e32 v57, v81, v35
	v_add_f32_e32 v37, v38, v37
	v_add_f32_e32 v38, v59, v48
	v_exp_f32_e32 v54, v54
	v_exp_f32_e32 v69, v57
	v_sub_f32_e32 v57, v97, v35
	v_add_f32_e32 v37, v38, v37
	v_add_f32_e32 v38, v61, v49
	v_exp_f32_e32 v57, v57
	v_add_f32_e32 v37, v38, v37
	v_add_f32_e32 v38, v63, v50
	v_add_f32_e32 v37, v38, v37
	v_add_f32_e32 v38, v65, v51
	v_add_f32_e32 v37, v38, v37
	v_add_f32_e32 v38, v67, v54
	v_add_f32_e32 v37, v38, v37
	v_add_f32_e32 v38, v69, v57
	v_add_f32_e32 v37, v38, v37
	v_sub_f32_e32 v34, v177, v35
	ds_bpermute_b32 v38, v197, v37
	v_exp_f32_e32 v34, v34
	v_cmp_gt_f32_e32 vcc, v174, v177
	s_cbranch_vccz .LBB0_1504
	v_pk_mul_f32 v[16:17], v[172:173], v[34:35] op_sel_hi:[1,0]
	v_pk_mul_f32 v[14:15], v[170:171], v[34:35] op_sel_hi:[1,0]
	v_pk_mul_f32 v[12:13], v[168:169], v[34:35] op_sel_hi:[1,0]
	v_pk_mul_f32 v[10:11], v[166:167], v[34:35] op_sel_hi:[1,0]
	v_pk_mul_f32 v[8:9], v[164:165], v[34:35] op_sel_hi:[1,0]
	v_pk_mul_f32 v[6:7], v[162:163], v[34:35] op_sel_hi:[1,0]
	v_pk_mul_f32 v[4:5], v[160:161], v[34:35] op_sel_hi:[1,0]
	v_pk_mul_f32 v[2:3], v[158:159], v[34:35] op_sel_hi:[1,0]
	v_pk_mul_f32 v[32:33], v[156:157], v[34:35] op_sel_hi:[1,0]
	v_pk_mul_f32 v[30:31], v[154:155], v[34:35] op_sel_hi:[1,0]
	v_pk_mul_f32 v[28:29], v[152:153], v[34:35] op_sel_hi:[1,0]
	v_pk_mul_f32 v[26:27], v[150:151], v[34:35] op_sel_hi:[1,0]
	v_pk_mul_f32 v[24:25], v[148:149], v[34:35] op_sel_hi:[1,0]
	v_pk_mul_f32 v[22:23], v[146:147], v[34:35] op_sel_hi:[1,0]
	v_pk_mul_f32 v[20:21], v[144:145], v[34:35] op_sel_hi:[1,0]
	v_pk_mul_f32 v[18:19], v[142:143], v[34:35] op_sel_hi:[1,0]

.LBB0_1508:
	v_med3_i32 v69, v82, 0, v192
	v_lshl_add_u32 v69, v69, 2, s3
	ds_read_b32 v83, v69
	v_add_u32_e32 v69, v68, v204
.LBB0_1509:
	v_med3_i32 v71, v69, 0, v192
	v_lshl_add_u32 v71, v71, 2, s3
	ds_read_b32 v71, v71
	v_add_u32_e32 v84, v70, v204
.LBB0_1510:
	v_med3_i32 v72, v84, 0, v192
	v_lshl_add_u32 v72, v72, 2, s3
	ds_read_b32 v85, v72
	v_add_u32_e32 v72, v68, v205
.LBB0_1511:
	v_med3_i32 v73, v72, 0, v192
	v_lshl_add_u32 v73, v73, 2, s3
	ds_read_b32 v73, v73
	v_add_u32_e32 v86, v70, v205
.LBB0_1512:
	v_med3_i32 v74, v86, 0, v192
	v_lshl_add_u32 v74, v74, 2, s3
	ds_read_b32 v87, v74
	v_add_u32_e32 v74, v68, v206
.LBB0_1513:
	v_med3_i32 v75, v74, 0, v192
	v_lshl_add_u32 v75, v75, 2, s3
	ds_read_b32 v75, v75
	v_add_u32_e32 v88, v70, v206
.LBB0_1514:
	v_med3_i32 v76, v88, 0, v192
	v_lshl_add_u32 v76, v76, 2, s3
	ds_read_b32 v89, v76
	v_add_u32_e32 v76, v68, v207
.LBB0_1515:
	v_med3_i32 v77, v76, 0, v192
	v_lshl_add_u32 v77, v77, 2, s3
	ds_read_b32 v77, v77
	v_add_u32_e32 v90, v70, v207
.LBB0_1516:
	v_med3_i32 v78, v90, 0, v192
	v_lshl_add_u32 v78, v78, 2, s3
	ds_read_b32 v91, v78
	v_add_u32_e32 v78, v68, v208
.LBB0_1517:
	v_med3_i32 v79, v78, 0, v192
	v_lshl_add_u32 v79, v79, 2, s3
	ds_read_b32 v79, v79
	v_add_u32_e32 v92, v70, v208
.LBB0_1518:
	v_med3_i32 v80, v92, 0, v192
	v_lshl_add_u32 v80, v80, 2, s3
	ds_read_b32 v93, v80
	v_add_u32_e32 v80, v68, v209
.LBB0_1519:
	v_med3_i32 v81, v80, 0, v192
	v_lshl_add_u32 v81, v81, 2, s3
	ds_read_b32 v81, v81
	v_add_u32_e32 v94, v70, v209
.LBB0_1520:
	v_med3_i32 v95, v94, 0, v192
	v_lshl_add_u32 v95, v95, 2, s3
	ds_read_b32 v95, v95
	v_add_u32_e32 v187, v68, v210
.LBB0_1521:
	v_med3_i32 v96, v187, 0, v192
	v_lshl_add_u32 v96, v96, 2, s3
	ds_read_b32 v188, v96
	v_add_u32_e32 v96, v70, v210
.LBB0_1522:
	v_med3_i32 v97, v96, 0, v192
	v_lshl_add_u32 v97, v97, 2, s3
	ds_read_b32 v97, v97
	v_add_u32_e32 v220, v68, v211
.LBB0_1523:
	v_med3_i32 v179, v220, 0, v192
	v_lshl_add_u32 v179, v179, 2, s3
	ds_read_b32 v221, v179
	v_add_u32_e32 v179, v70, v211
.LBB0_1524:
	v_med3_i32 v180, v179, 0, v192
	v_lshl_add_u32 v180, v180, 2, s3
	ds_read_b32 v180, v180
	v_add_u32_e32 v224, v68, v212
.LBB0_1525:
	v_med3_i32 v181, v224, 0, v192
	v_lshl_add_u32 v181, v181, 2, s3
	ds_read_b32 v225, v181
	v_add_u32_e32 v181, v70, v212
.LBB0_1526:
	v_med3_i32 v182, v181, 0, v192
	v_lshl_add_u32 v182, v182, 2, s3
	ds_read_b32 v182, v182
	v_add_u32_e32 v228, v68, v213
.LBB0_1527:
	v_med3_i32 v183, v228, 0, v192
	v_lshl_add_u32 v183, v183, 2, s3
	ds_read_b32 v229, v183
	v_add_u32_e32 v183, v70, v213
.LBB0_1528:
	v_med3_i32 v184, v183, 0, v192
	v_lshl_add_u32 v184, v184, 2, s3
	ds_read_b32 v184, v184
	v_add_u32_e32 v232, v68, v214
.LBB0_1529:
	v_med3_i32 v185, v232, 0, v192
	v_lshl_add_u32 v185, v185, 2, s3
	ds_read_b32 v233, v185
	v_add_u32_e32 v185, v70, v214
.LBB0_1530:
	v_med3_i32 v186, v185, 0, v192
	v_lshl_add_u32 v186, v186, 2, s3
	ds_read_b32 v186, v186
	v_add_u32_e32 v234, v68, v215
.LBB0_1531:
	v_med3_i32 v189, v234, 0, v192
	v_lshl_add_u32 v189, v189, 2, s3
	ds_read_b32 v235, v189
	v_add_u32_e32 v189, v70, v215
.LBB0_1532:
	v_med3_i32 v219, v189, 0, v192
	v_lshl_add_u32 v219, v219, 2, s3
	ds_read_b32 v219, v219
	v_add_u32_e32 v236, v68, v216
.LBB0_1533:
	v_med3_i32 v222, v236, 0, v192
	v_lshl_add_u32 v222, v222, 2, s3
	ds_read_b32 v237, v222
	v_add_u32_e32 v222, v70, v216
.LBB0_1534:
	v_med3_i32 v223, v222, 0, v192
	v_lshl_add_u32 v223, v223, 2, s3
	ds_read_b32 v223, v223
	v_add_u32_e32 v238, v68, v217
.LBB0_1535:
	v_med3_i32 v226, v238, 0, v192
	v_lshl_add_u32 v226, v226, 2, s3
	ds_read_b32 v239, v226
	v_add_u32_e32 v226, v70, v217
.LBB0_1536:
	v_med3_i32 v227, v226, 0, v192
	v_lshl_add_u32 v227, v227, 2, s3
	ds_read_b32 v227, v227
	v_add_u32_e32 v240, v68, v218
.LBB0_1537:
	v_med3_i32 v68, v240, 0, v192
	v_lshl_add_u32 v68, v68, 2, s3
	ds_read_b32 v241, v68
	v_add_u32_e32 v230, v70, v218
	s_and_b64 vcc, exec, s[10:11]
	v_mov_b32_e32 v231, v174
	s_cbranch_vccz .LBB0_1498
	s_branch .LBB0_1499

.LBB0_1581:
	v_max3_f32 v0, v191, v66, v82
	s_nop 8
	v_max_f32_e32 v35, v148, v148
	v_max3_f32 v0, v0, v67, v83
	v_max3_f32 v0, v0, v68, v84
	v_max3_f32 v0, v0, v69, v85
	v_max3_f32 v0, v0, v70, v86
	v_max3_f32 v0, v0, v71, v87
	v_max3_f32 v0, v0, v72, v88
	v_max3_f32 v0, v0, v73, v89
	v_max3_f32 v0, v0, v74, v90
	v_max3_f32 v0, v0, v75, v91
	v_max3_f32 v0, v0, v76, v92
	v_max3_f32 v0, v0, v77, v93
	v_max3_f32 v0, v0, v78, v94
	v_max3_f32 v0, v0, v79, v95
	v_max3_f32 v0, v0, v80, v96
	v_max3_f32 v0, v0, v81, v97
	ds_bpermute_b32 v34, v197, v0
	v_max_f32_e32 v0, v0, v0
	s_waitcnt lgkmcnt(0)
	v_max_f32_e32 v34, v34, v34
	v_max_f32_e32 v221, v0, v34
	v_max_f32_e32 v34, v35, v221
	v_sub_f32_e32 v0, v66, v34
	v_sub_f32_e32 v35, v82, v34
	v_exp_f32_e32 v52, v0
	v_sub_f32_e32 v0, v67, v34
	v_exp_f32_e32 v35, v35
	v_exp_f32_e32 v54, v0
	v_sub_f32_e32 v0, v83, v34
	v_sub_f32_e32 v39, v68, v34
	v_exp_f32_e32 v38, v0
	v_exp_f32_e32 v57, v39
	v_sub_f32_e32 v39, v84, v34
	v_sub_f32_e32 v40, v69, v34
	v_exp_f32_e32 v39, v39
	v_exp_f32_e32 v59, v40
	v_sub_f32_e32 v40, v85, v34
	v_sub_f32_e32 v41, v70, v34
	v_sub_f32_e32 v43, v72, v34
	v_exp_f32_e32 v40, v40
	v_exp_f32_e32 v61, v41
	v_sub_f32_e32 v41, v86, v34
	v_sub_f32_e32 v42, v71, v34
	v_exp_f32_e32 v65, v43
	v_sub_f32_e32 v43, v88, v34
	v_add_f32_e32 v36, v52, v35
	v_exp_f32_e32 v41, v41
	v_exp_f32_e32 v63, v42
	v_sub_f32_e32 v42, v87, v34
	v_exp_f32_e32 v44, v43
	v_sub_f32_e32 v43, v73, v34
	v_add_f32_e32 v36, 0, v36
	v_add_f32_e32 v37, v54, v38
	v_exp_f32_e32 v42, v42
	v_exp_f32_e32 v67, v43
	v_sub_f32_e32 v43, v89, v34
	v_add_f32_e32 v36, v37, v36
	v_add_f32_e32 v37, v57, v39
	v_exp_f32_e32 v46, v43
	v_sub_f32_e32 v43, v74, v34
	v_add_f32_e32 v36, v37, v36
	v_add_f32_e32 v37, v59, v40
	v_exp_f32_e32 v51, v43
	v_sub_f32_e32 v43, v90, v34
	v_sub_f32_e32 v45, v75, v34
	v_add_f32_e32 v36, v37, v36
	v_add_f32_e32 v37, v61, v41
	v_exp_f32_e32 v43, v43
	v_exp_f32_e32 v55, v45
	v_sub_f32_e32 v45, v91, v34
	v_sub_f32_e32 v47, v76, v34
	v_add_f32_e32 v36, v37, v36
	v_add_f32_e32 v37, v63, v42
	v_exp_f32_e32 v45, v45
	v_exp_f32_e32 v58, v47
	v_sub_f32_e32 v47, v92, v34
	v_sub_f32_e32 v48, v77, v34
	v_add_f32_e32 v36, v37, v36
	v_add_f32_e32 v37, v65, v44
	v_exp_f32_e32 v47, v47
	v_exp_f32_e32 v60, v48
	v_sub_f32_e32 v48, v93, v34
	v_sub_f32_e32 v49, v78, v34
	v_add_f32_e32 v36, v37, v36
	v_add_f32_e32 v37, v67, v46
	v_exp_f32_e32 v48, v48
	v_exp_f32_e32 v62, v49
	v_sub_f32_e32 v49, v94, v34
	v_sub_f32_e32 v50, v79, v34
	v_add_f32_e32 v36, v37, v36
	v_add_f32_e32 v37, v51, v43
	v_exp_f32_e32 v49, v49
	v_exp_f32_e32 v64, v50
	v_sub_f32_e32 v50, v95, v34
	v_sub_f32_e32 v53, v80, v34
	v_add_f32_e32 v36, v37, v36
	v_add_f32_e32 v37, v55, v45
	v_exp_f32_e32 v50, v50
	v_exp_f32_e32 v66, v53
	v_sub_f32_e32 v53, v96, v34
	v_sub_f32_e32 v56, v81, v34
	v_add_f32_e32 v36, v37, v36
	v_add_f32_e32 v37, v58, v47
	v_exp_f32_e32 v53, v53
	v_exp_f32_e32 v68, v56
	v_sub_f32_e32 v56, v97, v34
	v_add_f32_e32 v36, v37, v36
	v_add_f32_e32 v37, v60, v48
	v_exp_f32_e32 v56, v56
	v_add_f32_e32 v36, v37, v36
	v_add_f32_e32 v37, v62, v49
	v_add_f32_e32 v36, v37, v36
	v_add_f32_e32 v37, v64, v50
	v_add_f32_e32 v36, v37, v36
	v_add_f32_e32 v37, v66, v53
	v_add_f32_e32 v36, v37, v36
	v_add_f32_e32 v37, v68, v56
	v_add_f32_e32 v36, v37, v36
	v_sub_f32_e32 v0, v148, v34
	ds_bpermute_b32 v37, v197, v36
	v_exp_f32_e32 v0, v0
	v_cmp_gt_f32_e32 vcc, v221, v148
	s_cbranch_vccz .LBB0_1583
	v_pk_mul_f32 v[32:33], v[188:189], v[0:1] op_sel_hi:[1,0]
	v_pk_mul_f32 v[30:31], v[186:187], v[0:1] op_sel_hi:[1,0]
	v_pk_mul_f32 v[28:29], v[184:185], v[0:1] op_sel_hi:[1,0]
	v_pk_mul_f32 v[26:27], v[182:183], v[0:1] op_sel_hi:[1,0]
	v_pk_mul_f32 v[24:25], v[180:181], v[0:1] op_sel_hi:[1,0]
	v_pk_mul_f32 v[22:23], v[178:179], v[0:1] op_sel_hi:[1,0]
	v_pk_mul_f32 v[20:21], v[176:177], v[0:1] op_sel_hi:[1,0]
	v_pk_mul_f32 v[18:19], v[174:175], v[0:1] op_sel_hi:[1,0]
	v_pk_mul_f32 v[16:17], v[172:173], v[0:1] op_sel_hi:[1,0]
	v_pk_mul_f32 v[14:15], v[170:171], v[0:1] op_sel_hi:[1,0]
	v_pk_mul_f32 v[12:13], v[168:169], v[0:1] op_sel_hi:[1,0]
	v_pk_mul_f32 v[10:11], v[166:167], v[0:1] op_sel_hi:[1,0]
	v_pk_mul_f32 v[8:9], v[164:165], v[0:1] op_sel_hi:[1,0]
	v_pk_mul_f32 v[6:7], v[162:163], v[0:1] op_sel_hi:[1,0]
	v_pk_mul_f32 v[4:5], v[160:161], v[0:1] op_sel_hi:[1,0]
	v_pk_mul_f32 v[2:3], v[158:159], v[0:1] op_sel_hi:[1,0]

.LBB0_1587:
	v_med3_i32 v68, v85, 0, v192
	v_lshl_add_u32 v68, v68, 2, s3
	ds_read_b32 v82, v68
	v_add_u32_e32 v68, v70, v204
.LBB0_1588:
	v_med3_i32 v69, v68, 0, v192
	v_lshl_add_u32 v69, v69, 2, s3
	ds_read_b32 v69, v69
	v_add_u32_e32 v83, v71, v204
.LBB0_1589:
	v_med3_i32 v72, v83, 0, v192
	v_lshl_add_u32 v72, v72, 2, s3
	ds_read_b32 v84, v72
	v_add_u32_e32 v72, v70, v205
.LBB0_1590:
	v_med3_i32 v73, v72, 0, v192
	v_lshl_add_u32 v73, v73, 2, s3
	ds_read_b32 v73, v73
	v_add_u32_e32 v86, v71, v205
.LBB0_1591:
	v_med3_i32 v74, v86, 0, v192
	v_lshl_add_u32 v74, v74, 2, s3
	ds_read_b32 v87, v74
	v_add_u32_e32 v74, v70, v206
.LBB0_1592:
	v_med3_i32 v75, v74, 0, v192
	v_lshl_add_u32 v75, v75, 2, s3
	ds_read_b32 v75, v75
	v_add_u32_e32 v88, v71, v206
.LBB0_1593:
	v_med3_i32 v76, v88, 0, v192
	v_lshl_add_u32 v76, v76, 2, s3
	ds_read_b32 v89, v76
	v_add_u32_e32 v76, v70, v207
.LBB0_1594:
	v_med3_i32 v77, v76, 0, v192
	v_lshl_add_u32 v77, v77, 2, s3
	ds_read_b32 v77, v77
	v_add_u32_e32 v90, v71, v207
.LBB0_1595:
	v_med3_i32 v78, v90, 0, v192
	v_lshl_add_u32 v78, v78, 2, s3
	ds_read_b32 v91, v78
	v_add_u32_e32 v78, v70, v208
.LBB0_1596:
	v_med3_i32 v79, v78, 0, v192
	v_lshl_add_u32 v79, v79, 2, s3
	ds_read_b32 v79, v79
	v_add_u32_e32 v92, v71, v208
.LBB0_1597:
	v_med3_i32 v80, v92, 0, v192
	v_lshl_add_u32 v80, v80, 2, s3
	ds_read_b32 v93, v80
	v_add_u32_e32 v80, v70, v209
.LBB0_1598:
	v_med3_i32 v81, v80, 0, v192
	v_lshl_add_u32 v81, v81, 2, s3
	ds_read_b32 v81, v81
	v_add_u32_e32 v94, v71, v209
.LBB0_1599:
	v_med3_i32 v95, v94, 0, v192
	v_lshl_add_u32 v95, v95, 2, s3
	ds_read_b32 v95, v95
	v_add_u32_e32 v237, v70, v210
.LBB0_1600:
	v_med3_i32 v96, v237, 0, v192
	v_lshl_add_u32 v96, v96, 2, s3
	ds_read_b32 v238, v96
	v_add_u32_e32 v96, v71, v210
.LBB0_1601:
	v_med3_i32 v97, v96, 0, v192
	v_lshl_add_u32 v97, v97, 2, s3
	ds_read_b32 v97, v97
	v_add_u32_e32 v239, v70, v211
.LBB0_1602:
	v_med3_i32 v221, v239, 0, v192
	v_lshl_add_u32 v221, v221, 2, s3
	ds_read_b32 v240, v221
	v_add_u32_e32 v221, v71, v211
.LBB0_1603:
	v_med3_i32 v222, v221, 0, v192
	v_lshl_add_u32 v222, v222, 2, s3
	ds_read_b32 v222, v222
	v_add_u32_e32 v241, v70, v212
.LBB0_1604:
	v_med3_i32 v223, v241, 0, v192
	v_lshl_add_u32 v223, v223, 2, s3
	ds_read_b32 v242, v223
	v_add_u32_e32 v223, v71, v212
.LBB0_1605:
	v_med3_i32 v224, v223, 0, v192
	v_lshl_add_u32 v224, v224, 2, s3
	ds_read_b32 v224, v224
	v_add_u32_e32 v243, v70, v213
.LBB0_1606:
	v_med3_i32 v225, v243, 0, v192
	v_lshl_add_u32 v225, v225, 2, s3
	ds_read_b32 v244, v225
	v_add_u32_e32 v225, v71, v213
.LBB0_1607:
	v_med3_i32 v226, v225, 0, v192
	v_lshl_add_u32 v226, v226, 2, s3
	ds_read_b32 v226, v226
	v_add_u32_e32 v245, v70, v214
.LBB0_1608:
	v_med3_i32 v227, v245, 0, v192
	v_lshl_add_u32 v227, v227, 2, s3
	ds_read_b32 v246, v227
	v_add_u32_e32 v227, v71, v214
.LBB0_1609:
	v_med3_i32 v228, v227, 0, v192
	v_lshl_add_u32 v228, v228, 2, s3
	ds_read_b32 v228, v228
	v_add_u32_e32 v247, v70, v215
.LBB0_1610:
	v_med3_i32 v229, v247, 0, v192
	v_lshl_add_u32 v229, v229, 2, s3
	ds_read_b32 v248, v229
	v_add_u32_e32 v229, v71, v215
.LBB0_1611:
	v_med3_i32 v230, v229, 0, v192
	v_lshl_add_u32 v230, v230, 2, s3
	ds_read_b32 v230, v230
	v_add_u32_e32 v249, v70, v216
.LBB0_1612:
	v_med3_i32 v231, v249, 0, v192
	v_lshl_add_u32 v231, v231, 2, s3
	ds_read_b32 v250, v231
	v_add_u32_e32 v231, v71, v216
.LBB0_1613:
	v_med3_i32 v232, v231, 0, v192
	v_lshl_add_u32 v232, v232, 2, s3
	ds_read_b32 v232, v232
	v_add_u32_e32 v251, v70, v217
.LBB0_1614:
	v_med3_i32 v233, v251, 0, v192
	v_lshl_add_u32 v233, v233, 2, s3
	ds_read_b32 v252, v233
	v_add_u32_e32 v233, v71, v217
.LBB0_1615:
	v_med3_i32 v234, v233, 0, v192
	v_lshl_add_u32 v234, v234, 2, s3
	ds_read_b32 v234, v234
	v_add_u32_e32 v253, v70, v218
.LBB0_1616:
	v_med3_i32 v70, v253, 0, v192
	v_lshl_add_u32 v70, v70, 2, s3
	ds_read_b32 v254, v70
	v_add_u32_e32 v235, v71, v218
	s_and_b64 vcc, exec, s[8:9]
	v_mov_b32_e32 v236, v0
	s_cbranch_vccz .LBB0_1577
	s_branch .LBB0_1578

.LBB0_2633:
	v_max3_f32 v0, v193, v96, v80
	v_max_f32_e32 v208, v207, v207
	v_max3_f32 v0, v0, v97, v81
	v_max3_f32 v0, v0, v98, v82
	v_max3_f32 v0, v0, v99, v83
	v_max3_f32 v0, v0, v100, v84
	v_max3_f32 v0, v0, v101, v85
	v_max3_f32 v0, v0, v102, v86
	v_max3_f32 v0, v0, v103, v87
	v_max3_f32 v0, v0, v104, v88
	v_max3_f32 v0, v0, v105, v89
	v_max3_f32 v0, v0, v106, v90
	v_max3_f32 v0, v0, v107, v91
	v_max3_f32 v0, v0, v108, v92
	v_max3_f32 v0, v0, v109, v93
	v_max3_f32 v0, v0, v110, v94
	v_max3_f32 v0, v0, v111, v95
	ds_bpermute_b32 v15, v205, v0
	v_max_f32_e32 v0, v0, v0
	s_waitcnt lgkmcnt(0)
	v_max_f32_e32 v15, v15, v15
	v_max_f32_e32 v216, v0, v15
	v_max_f32_e32 v15, v208, v216
	v_sub_f32_e32 v0, v96, v15
	v_sub_f32_e32 v80, v80, v15
	v_exp_f32_e32 v208, v0
	v_sub_f32_e32 v0, v97, v15
	v_exp_f32_e32 v80, v80
	v_exp_f32_e32 v209, v0
	v_sub_f32_e32 v0, v81, v15
	v_exp_f32_e32 v81, v0
	v_sub_f32_e32 v98, v98, v15
	v_sub_f32_e32 v82, v82, v15
	v_exp_f32_e32 v210, v98
	v_exp_f32_e32 v82, v82
	v_add_f32_e32 v96, v208, v80
	v_sub_f32_e32 v98, v99, v15
	v_sub_f32_e32 v83, v83, v15
	v_add_f32_e32 v96, 0, v96
	v_add_f32_e32 v97, v209, v81
	v_exp_f32_e32 v211, v98
	v_exp_f32_e32 v83, v83
	v_add_f32_e32 v96, v97, v96
	v_add_f32_e32 v97, v210, v82
	v_add_f32_e32 v98, v97, v96
	v_sub_f32_e32 v96, v100, v15
	v_sub_f32_e32 v84, v84, v15
	v_exp_f32_e32 v212, v96
	v_exp_f32_e32 v96, v84
	v_sub_f32_e32 v84, v101, v15
	v_add_f32_e32 v99, v211, v83
	v_exp_f32_e32 v213, v84
	v_sub_f32_e32 v84, v85, v15
	v_exp_f32_e32 v97, v84
	v_add_f32_e32 v84, v99, v98
	v_sub_f32_e32 v98, v102, v15
	v_sub_f32_e32 v86, v86, v15
	v_exp_f32_e32 v214, v98
	v_exp_f32_e32 v98, v86
	v_add_f32_e32 v85, v212, v96
	v_add_f32_e32 v84, v85, v84
	v_add_f32_e32 v85, v213, v97
	v_sub_f32_e32 v86, v103, v15
	v_exp_f32_e32 v215, v86
	v_sub_f32_e32 v86, v87, v15
	v_add_f32_e32 v84, v85, v84
	v_add_f32_e32 v85, v214, v98
	v_exp_f32_e32 v99, v86
	v_add_f32_e32 v86, v85, v84
	v_sub_f32_e32 v84, v104, v15
	v_exp_f32_e32 v100, v84
	v_sub_f32_e32 v84, v88, v15
	v_exp_f32_e32 v84, v84
	v_add_f32_e32 v87, v215, v99
	v_sub_f32_e32 v85, v105, v15
	v_add_f32_e32 v86, v87, v86
	v_add_f32_e32 v87, v100, v84
	v_exp_f32_e32 v101, v85
	v_sub_f32_e32 v85, v89, v15
	v_add_f32_e32 v88, v87, v86
	v_sub_f32_e32 v86, v106, v15
	v_exp_f32_e32 v85, v85
	v_exp_f32_e32 v102, v86
	v_sub_f32_e32 v86, v90, v15
	v_exp_f32_e32 v86, v86
	v_add_f32_e32 v89, v101, v85
	v_sub_f32_e32 v87, v107, v15
	v_add_f32_e32 v88, v89, v88
	v_add_f32_e32 v89, v102, v86
	v_exp_f32_e32 v103, v87
	v_sub_f32_e32 v87, v91, v15
	v_add_f32_e32 v90, v89, v88
	v_sub_f32_e32 v88, v108, v15
	v_exp_f32_e32 v87, v87
	v_exp_f32_e32 v104, v88
	v_sub_f32_e32 v88, v92, v15
	v_exp_f32_e32 v88, v88
	v_add_f32_e32 v91, v103, v87
	v_sub_f32_e32 v89, v109, v15
	v_add_f32_e32 v90, v91, v90
	v_add_f32_e32 v91, v104, v88
	v_exp_f32_e32 v92, v89
	v_sub_f32_e32 v89, v93, v15
	v_add_f32_e32 v105, v91, v90
	v_sub_f32_e32 v90, v110, v15
	v_exp_f32_e32 v89, v89
	v_exp_f32_e32 v93, v90
	v_sub_f32_e32 v90, v94, v15
	v_sub_f32_e32 v91, v111, v15
	v_exp_f32_e32 v90, v90
	v_exp_f32_e32 v94, v91
	v_sub_f32_e32 v91, v95, v15
	v_exp_f32_e32 v91, v91
	v_add_f32_e32 v106, v92, v89
	v_add_f32_e32 v95, v106, v105
	v_add_f32_e32 v105, v93, v90
	v_add_f32_e32 v95, v105, v95
	v_add_f32_e32 v105, v94, v91
	v_add_f32_e32 v95, v105, v95
	v_sub_f32_e32 v0, v207, v15
	ds_bpermute_b32 v105, v205, v95
	v_exp_f32_e32 v0, v0
	v_cmp_gt_f32_e32 vcc, v216, v207
	s_cbranch_vccz .LBB0_2635
	v_pk_mul_f32 v[78:79], v[78:79], v[0:1] op_sel_hi:[1,0]
	v_pk_mul_f32 v[76:77], v[76:77], v[0:1] op_sel_hi:[1,0]
	v_pk_mul_f32 v[74:75], v[74:75], v[0:1] op_sel_hi:[1,0]
	v_pk_mul_f32 v[72:73], v[72:73], v[0:1] op_sel_hi:[1,0]
	v_pk_mul_f32 v[70:71], v[70:71], v[0:1] op_sel_hi:[1,0]
	v_pk_mul_f32 v[68:69], v[68:69], v[0:1] op_sel_hi:[1,0]
	v_pk_mul_f32 v[66:67], v[66:67], v[0:1] op_sel_hi:[1,0]
	v_pk_mul_f32 v[64:65], v[64:65], v[0:1] op_sel_hi:[1,0]
	v_pk_mul_f32 v[62:63], v[62:63], v[0:1] op_sel_hi:[1,0]
	v_pk_mul_f32 v[60:61], v[60:61], v[0:1] op_sel_hi:[1,0]
	v_pk_mul_f32 v[58:59], v[58:59], v[0:1] op_sel_hi:[1,0]
	v_pk_mul_f32 v[56:57], v[56:57], v[0:1] op_sel_hi:[1,0]
	v_pk_mul_f32 v[54:55], v[54:55], v[0:1] op_sel_hi:[1,0]
	v_pk_mul_f32 v[52:53], v[52:53], v[0:1] op_sel_hi:[1,0]
	v_pk_mul_f32 v[50:51], v[50:51], v[0:1] op_sel_hi:[1,0]
	v_pk_mul_f32 v[48:49], v[48:49], v[0:1] op_sel_hi:[1,0]
	v_pk_mul_f32 v[46:47], v[46:47], v[0:1] op_sel_hi:[1,0]
	v_pk_mul_f32 v[44:45], v[44:45], v[0:1] op_sel_hi:[1,0]
	v_pk_mul_f32 v[42:43], v[42:43], v[0:1] op_sel_hi:[1,0]
	v_pk_mul_f32 v[40:41], v[40:41], v[0:1] op_sel_hi:[1,0]
	v_pk_mul_f32 v[38:39], v[38:39], v[0:1] op_sel_hi:[1,0]
	v_pk_mul_f32 v[36:37], v[36:37], v[0:1] op_sel_hi:[1,0]
	v_pk_mul_f32 v[34:35], v[34:35], v[0:1] op_sel_hi:[1,0]
	v_pk_mul_f32 v[32:33], v[32:33], v[0:1] op_sel_hi:[1,0]
	v_pk_mul_f32 v[30:31], v[30:31], v[0:1] op_sel_hi:[1,0]
	v_pk_mul_f32 v[28:29], v[28:29], v[0:1] op_sel_hi:[1,0]
	v_pk_mul_f32 v[26:27], v[26:27], v[0:1] op_sel_hi:[1,0]
	v_pk_mul_f32 v[24:25], v[24:25], v[0:1] op_sel_hi:[1,0]
	v_pk_mul_f32 v[22:23], v[22:23], v[0:1] op_sel_hi:[1,0]
	v_pk_mul_f32 v[20:21], v[20:21], v[0:1] op_sel_hi:[1,0]
	v_pk_mul_f32 v[18:19], v[18:19], v[0:1] op_sel_hi:[1,0]
	v_pk_mul_f32 v[16:17], v[16:17], v[0:1] op_sel_hi:[1,0]
